# attention loop: exact-max path moved out of line so the common (no-max) softmax path falls through without a taken branch
# speedup vs baseline: 1.0140x; 1.0140x over previous
.Latt_loop:
	s_setprio 1
	s_waitcnt lgkmcnt(3)
	v_mfma_f32_32x32x16_bf16 v[96:111], v[128:131], v[144:147], 0
	ds_read_b128 v[128:131], v12 offset:4096
	s_waitcnt lgkmcnt(3)
	v_mfma_f32_32x32x16_bf16 v[80:95], v[132:135], v[144:147], 0
	ds_read_b128 v[132:135], v12 offset:4608
	s_mov_b32 m0, s51
	s_nop 0
	global_load_lds_dwordx4 v237, s[64:65]
	s_add_u32 s64, s64, 0x200000
	s_addc_u32 s65, s65, 0
	s_waitcnt lgkmcnt(3)
	v_mfma_f32_32x32x16_bf16 v[96:111], v[136:139], v[148:151], v[96:111]
	ds_read_b128 v[136:139], v12 offset:6144
	s_waitcnt lgkmcnt(3)
	v_mfma_f32_32x32x16_bf16 v[80:95], v[140:143], v[148:151], v[80:95]
	ds_read_b128 v[140:143], v12 offset:6656
	s_add_i32 m0, s51, 0x2000
	s_nop 0
	global_load_lds_dwordx4 v237, s[64:65]
	s_waitcnt lgkmcnt(3)
	v_mfma_f32_32x32x16_bf16 v[96:111], v[128:131], v[152:155], v[96:111]
	ds_read_b128 v[238:241], v13 offset:49152
	s_waitcnt lgkmcnt(3)
	v_mfma_f32_32x32x16_bf16 v[80:95], v[132:135], v[152:155], v[80:95]
	ds_read_b128 v[242:245], v13 offset:53248
	s_mov_b32 m0, s57
	s_nop 0
	global_load_lds_dwordx4 v237, s[6:7]
	s_add_u32 s6, s6, 0x2000
	s_addc_u32 s7, s7, 0
	s_waitcnt lgkmcnt(3)
	v_mfma_f32_32x32x16_bf16 v[96:111], v[136:139], v[156:159], v[96:111]
	ds_read_b128 v[246:249], v13 offset:57344
	s_waitcnt lgkmcnt(3)
	v_mfma_f32_32x32x16_bf16 v[80:95], v[140:143], v[156:159], v[80:95]
	ds_read_b128 v[250:253], v13 offset:61440
	s_add_i32 m0, s57, 0x2000
	s_nop 0
	global_load_lds_dwordx4 v237, s[6:7]
	s_waitcnt lgkmcnt(3)
	v_mfma_f32_32x32x16_bf16 v[64:79], v[112:115], v[238:241], v[64:79]
	ds_read_b128 v[238:241], v13 offset:50176
	s_waitcnt lgkmcnt(3)
	v_mfma_f32_32x32x16_bf16 v[48:63], v[112:115], v[242:245], v[48:63]
	ds_read_b128 v[242:245], v13 offset:54272
	s_waitcnt lgkmcnt(3)
	v_mfma_f32_32x32x16_bf16 v[32:47], v[112:115], v[246:249], v[32:47]
	ds_read_b128 v[246:249], v13 offset:58368
	s_waitcnt lgkmcnt(3)
	v_mfma_f32_32x32x16_bf16 v[16:31], v[112:115], v[250:253], v[16:31]
	ds_read_b128 v[250:253], v13 offset:62464
	s_waitcnt lgkmcnt(3)
	v_mfma_f32_32x32x16_bf16 v[64:79], v[116:119], v[238:241], v[64:79]
	ds_read_b128 v[238:241], v13 offset:51200
	s_waitcnt lgkmcnt(3)
	v_mfma_f32_32x32x16_bf16 v[48:63], v[116:119], v[242:245], v[48:63]
	ds_read_b128 v[242:245], v13 offset:55296
	s_waitcnt lgkmcnt(3)
	v_mfma_f32_32x32x16_bf16 v[32:47], v[116:119], v[246:249], v[32:47]
	ds_read_b128 v[246:249], v13 offset:59392
	s_waitcnt lgkmcnt(3)
	v_mfma_f32_32x32x16_bf16 v[16:31], v[116:119], v[250:253], v[16:31]
	ds_read_b128 v[250:253], v13 offset:63488
	s_waitcnt lgkmcnt(3)
	v_mfma_f32_32x32x16_bf16 v[64:79], v[120:123], v[238:241], v[64:79]
	ds_read_b128 v[238:241], v13 offset:52224
	s_waitcnt lgkmcnt(3)
	v_mfma_f32_32x32x16_bf16 v[48:63], v[120:123], v[242:245], v[48:63]
	ds_read_b128 v[242:245], v13 offset:56320
	s_waitcnt lgkmcnt(3)
	v_mfma_f32_32x32x16_bf16 v[32:47], v[120:123], v[246:249], v[32:47]
	ds_read_b128 v[246:249], v13 offset:60416
	s_waitcnt lgkmcnt(3)
	v_mfma_f32_32x32x16_bf16 v[16:31], v[120:123], v[250:253], v[16:31]
	ds_read_b128 v[250:253], v13 offset:64512
	s_waitcnt lgkmcnt(3)
	v_mfma_f32_32x32x16_bf16 v[64:79], v[124:127], v[238:241], v[64:79]
	s_waitcnt lgkmcnt(2)
	v_mfma_f32_32x32x16_bf16 v[48:63], v[124:127], v[242:245], v[48:63]
	s_waitcnt lgkmcnt(1)
	v_mfma_f32_32x32x16_bf16 v[32:47], v[124:127], v[246:249], v[32:47]
	s_waitcnt lgkmcnt(0)
	v_mfma_f32_32x32x16_bf16 v[16:31], v[124:127], v[250:253], v[16:31]
	s_barrier
	s_setprio 0
	s_add_i32 s45, s45, 1
	s_mov_b32 s6, s46
	s_mov_b32 s46, s47
	s_mov_b32 s47, s54
	s_mov_b32 s54, s6
	s_cmp_ge_u32 s45, s11
	s_cbranch_scc1 .Latt_last
	s_and_b64 vcc, exec, s[0:1]
	s_cbranch_vccnz .Latt_exact

.Latt_exact:
	v_max3_f32 v0, v96, v97, v98
	v_max3_f32 v2, v80, v81, v82
	s_andn2_b64 vcc, exec, s[2:3]
	v_max3_f32 v0, v0, v99, v100
	v_max3_f32 v2, v2, v83, v84
	s_nop 0
	v_max3_f32 v0, v0, v101, v102
	v_max3_f32 v2, v2, v85, v86
	s_nop 0
	v_max3_f32 v0, v0, v103, v104
	v_max3_f32 v2, v2, v87, v88
	s_nop 0
	v_max3_f32 v0, v0, v105, v106
	v_max3_f32 v2, v2, v89, v90
	s_nop 0
	v_max3_f32 v0, v0, v107, v108
	v_max3_f32 v2, v2, v91, v92
	s_nop 0
	v_max3_f32 v0, v0, v109, v110
	v_max3_f32 v2, v2, v93, v94
	s_nop 0
	v_max3_f32 v0, v0, v111, v95
	s_nop 0
	v_max_f32_e32 v0, v0, v2
	s_nop 0
	v_mov_b32_e32 v2, v0
	s_nop 1
	v_permlane32_swap_b32_e32 v0, v2
	v_max_f32_e32 v0, v0, v2
	s_cbranch_vccnz .Latt_x1
	v_sub_f32_e32 v111, v111, v235
	v_sub_f32_e32 v110, v110, v235
	v_sub_f32_e32 v109, v109, v235
	v_sub_f32_e32 v108, v108, v235
	v_sub_f32_e32 v107, v107, v235
	v_sub_f32_e32 v106, v106, v235
	v_sub_f32_e32 v105, v105, v235
	v_sub_f32_e32 v104, v104, v235
	v_sub_f32_e32 v103, v103, v235
	v_sub_f32_e32 v102, v102, v235
	v_sub_f32_e32 v101, v101, v235
	v_sub_f32_e32 v100, v100, v235
	v_sub_f32_e32 v99, v99, v235
	v_sub_f32_e32 v98, v98, v235
	v_sub_f32_e32 v97, v97, v235
	v_sub_f32_e32 v96, v96, v235
	v_sub_f32_e32 v95, v95, v235
	v_sub_f32_e32 v94, v94, v235
	v_sub_f32_e32 v93, v93, v235
	v_sub_f32_e32 v92, v92, v235
	v_sub_f32_e32 v91, v91, v235
	v_sub_f32_e32 v90, v90, v235
	v_sub_f32_e32 v89, v89, v235
	v_sub_f32_e32 v88, v88, v235
	v_sub_f32_e32 v87, v87, v235
	v_sub_f32_e32 v86, v86, v235
	v_sub_f32_e32 v85, v85, v235
	v_sub_f32_e32 v84, v84, v235
	v_sub_f32_e32 v83, v83, v235
	v_sub_f32_e32 v82, v82, v235
	v_sub_f32_e32 v81, v81, v235
	v_sub_f32_e32 v80, v80, v235
.Latt_x1:
	v_sub_f32_e32 v0, v0, v235
	v_cmp_lt_f32_e32 vcc, s41, v0
	s_cbranch_vccz .Latt_exp
	v_max_f32_e32 v0, v0, v0
	v_max_f32_e32 v0, 0, v0
	v_exp_f32_e64 v2, -v0
	s_and_saveexec_b64 s[2:3], s[4:5]
	ds_write_b32 v205, v2
	s_or_b64 exec, exec, s[2:3]
	v_sub_f32_e32 v111, v111, v0
	v_sub_f32_e32 v110, v110, v0
	v_sub_f32_e32 v109, v109, v0
	v_sub_f32_e32 v108, v108, v0
	v_sub_f32_e32 v107, v107, v0
	v_sub_f32_e32 v106, v106, v0
	v_sub_f32_e32 v105, v105, v0
	v_sub_f32_e32 v104, v104, v0
	v_sub_f32_e32 v103, v103, v0
	v_sub_f32_e32 v102, v102, v0
	v_sub_f32_e32 v101, v101, v0
	v_sub_f32_e32 v100, v100, v0
	v_sub_f32_e32 v99, v99, v0
	v_sub_f32_e32 v98, v98, v0
	v_sub_f32_e32 v97, v97, v0
	v_sub_f32_e32 v96, v96, v0
	v_sub_f32_e32 v95, v95, v0
	v_sub_f32_e32 v94, v94, v0
	v_sub_f32_e32 v93, v93, v0
	v_sub_f32_e32 v92, v92, v0
	v_sub_f32_e32 v91, v91, v0
	v_sub_f32_e32 v90, v90, v0
	v_sub_f32_e32 v89, v89, v0
	v_sub_f32_e32 v88, v88, v0
	v_sub_f32_e32 v87, v87, v0
	v_sub_f32_e32 v86, v86, v0
	v_sub_f32_e32 v85, v85, v0
	v_sub_f32_e32 v84, v84, v0
	v_sub_f32_e32 v83, v83, v0
	v_sub_f32_e32 v82, v82, v0
	v_sub_f32_e32 v81, v81, v0
	v_sub_f32_e32 v80, v80, v0
	v_add_f32_e32 v235, v235, v0
	s_waitcnt lgkmcnt(0)
	v_add_u32_e32 v0, s34, v174
	v_mul_f32_e32 v236, v236, v2
	ds_read_b128 v[2:5], v0
	ds_read_b128 v[6:9], v0 offset:32
	ds_read_b128 v[10:13], v0 offset:64
	ds_read_b128 v[112:115], v0 offset:96
	s_mov_b64 s[2:3], -1
	s_waitcnt lgkmcnt(3)
	v_pk_mul_f32 v[66:67], v[66:67], v[4:5]
	s_waitcnt lgkmcnt(2)
	v_pk_mul_f32 v[68:69], v[68:69], v[6:7]
	s_waitcnt lgkmcnt(1)
	v_pk_mul_f32 v[72:73], v[72:73], v[10:11]
	s_waitcnt lgkmcnt(0)
	v_pk_mul_f32 v[76:77], v[76:77], v[112:113]
	v_pk_mul_f32 v[78:79], v[78:79], v[114:115]
	v_pk_mul_f32 v[74:75], v[74:75], v[12:13]
	v_pk_mul_f32 v[70:71], v[70:71], v[8:9]
	v_pk_mul_f32 v[64:65], v[64:65], v[2:3]
	v_pk_mul_f32 v[60:61], v[60:61], v[112:113]
	v_pk_mul_f32 v[56:57], v[56:57], v[10:11]
	v_pk_mul_f32 v[52:53], v[52:53], v[6:7]
	v_pk_mul_f32 v[62:63], v[62:63], v[114:115]
	v_pk_mul_f32 v[58:59], v[58:59], v[12:13]
	v_pk_mul_f32 v[54:55], v[54:55], v[8:9]
	v_pk_mul_f32 v[50:51], v[50:51], v[4:5]
	v_pk_mul_f32 v[48:49], v[48:49], v[2:3]
	v_pk_mul_f32 v[44:45], v[44:45], v[112:113]
	v_pk_mul_f32 v[40:41], v[40:41], v[10:11]
	v_pk_mul_f32 v[36:37], v[36:37], v[6:7]
	v_pk_mul_f32 v[46:47], v[46:47], v[114:115]
	v_pk_mul_f32 v[42:43], v[42:43], v[12:13]
	v_pk_mul_f32 v[38:39], v[38:39], v[8:9]
	v_pk_mul_f32 v[34:35], v[34:35], v[4:5]
	v_pk_mul_f32 v[32:33], v[32:33], v[2:3]
	v_pk_mul_f32 v[28:29], v[28:29], v[112:113]
	v_pk_mul_f32 v[24:25], v[24:25], v[10:11]
	v_pk_mul_f32 v[20:21], v[20:21], v[6:7]
	v_pk_mul_f32 v[30:31], v[30:31], v[114:115]
	v_pk_mul_f32 v[26:27], v[26:27], v[12:13]
	v_pk_mul_f32 v[22:23], v[22:23], v[8:9]
	v_pk_mul_f32 v[18:19], v[18:19], v[4:5]
	v_pk_mul_f32 v[16:17], v[16:17], v[2:3]
	s_branch .Latt_exp
